# NSA unit prologue: compressed image rows, Q fragments, gates requested together (one memory round trip instead of three), image rows written to LDS before the prologue barrier
# speedup vs baseline: 1.0033x; 1.0004x over previous
; #define LAS __attribute__((address_space(3)))
; DI int off64(int row, int ch) { return row * 128 + ((ch ^ swz64(row)) << 4); }
; DI f32x16 zero16() { f32x16 z; for (int i = 0; i < 16; ++i) z[i] = 0.f; return z; }
; DI void nsa_unit(const Args& a, LAS unsigned char* lds, int b, int g, int jb) {
;     ...
;     { const bf16_t* kc = KC + ((size_t)(b * 2 + g) * 128) * 64; const bf16_t* vc = kc + (size_t)AROWS * 64;
; #pragma unroll
;       for (int i = 0; i < 2; ++i) { const int idx = tid + 512 * i, rw = idx >> 3, ch = idx & 7;
;           if (rw < 32 * (((4 * jb + 2) >> 5) + 1)) {
;           *(LAS u32x4*)(lds + off64(rw, ch)) = *(const u32x4*)(kc + (size_t)rw * 64 + ch * 8); *(LAS u32x4*)(lds + 16384 + off64(rw, ch)) = *(const u32x4*)(vc + (size_t)rw * 64 + ch * 8); } } }
;     bf16x8 qf[4];
; #pragma unroll
;     for (int ks = 0; ks < 4; ++ks) qf[ks] = *(const bf16x8*)(QA + row * 512 + (g * 4 + hh) * 64 + 16 * ks + 8 * h2);
;     const float* ga = (const float*)(ws + WS_GA) + row * 32 + (g * 4 + hh) * 3;
;     const float gate_c = ga[0], gate_s = ga[1], gate_w = ga[2];
;     const float c31 = rbp[31 * 8 + g * 4 + hh] * LOG2E;
;     const LAS float* lut = LUT + hh * LUTR_N;
;     __syncthreads();
;     float* oscr = (float*)(ws + WS_NSCR) + ((size_t)(blockIdx.x * 8 + wave) * 32) * 64 + lane;
;     {
;         f32x16 OUT[2]; OUT[0] = zero16(); OUT[1] = zero16();
;         const LAS unsigned char* Ks = lds; const LAS unsigned char* Vs = lds + 16384;
;         f32x16 S[4];
;         const int nrb = ((4 * jb + 2) >> 5) + 1;
; #pragma unroll
;         for (int rb = 0; rb < 4; ++rb) { if (rb < nrb) S[rb] = qk64_rb(Ks, rb, qf, r, h2); else S[rb] = zero16(); }
.LBB0_1779:
	s_lshl_b32 s4, s17, 14
	s_lshl_b32 s5, s14, 15
	s_or_b32 s4, s5, s4
	s_add_u32 s4, s55, s4
	s_addc_u32 s5, s56, 0
	s_lshl_b32 s6, s73, 2
	s_and_b32 s6, s6, 0xe0
	v_lshlrev_b32_e32 v4, 4, v3
	v_mov_b32_e32 v5, v2
	s_add_i32 s6, s6, 32
	v_lshl_add_u64 v[6:7], s[4:5], 0, v[4:5]
	s_mov_b64 s[4:5], 0x840000
	v_ashrrev_i32_e32 v8, 3, v92
	v_lshl_add_u64 v[4:5], v[6:7], 0, s[4:5]
	v_cmp_gt_i32_e32 vcc, s6, v8
	s_and_saveexec_b64 s[4:5], vcc
	s_cbranch_execz .LBB0_1781
	v_ashrrev_i32_e32 v9, 31, v8
	v_lshlrev_b64 v[10:11], 7, v[8:9]
	v_lshl_add_u64 v[12:13], v[6:7], 0, v[10:11]
	v_lshl_add_u64 v[14:15], v[4:5], 0, v[10:11]
	global_load_dwordx4 v[20:23], v[12:13], off
	s_nop 0
	global_load_dwordx4 v[24:27], v[14:15], off
	v_lshlrev_b32_e32 v18, 1, v8
	v_lshlrev_b32_e32 v9, 7, v8
	v_bfe_u32 v8, v8, 2, 2
	v_and_b32_e32 v18, 4, v18
	v_bitop3_b32 v8, v18, v3, v8 bitop3:0x36
	v_lshl_or_b32 v8, v8, 4, v9
	v_add_u32_e32 v36, 0, v8
.LBB0_1781:
	s_or_b64 exec, exec, s[4:5]
	v_add_u32_e32 v8, 0x200, v92
	v_ashrrev_i32_e32 v8, 3, v8
	v_cmp_gt_i32_e32 vcc, s6, v8
	s_and_saveexec_b64 s[4:5], vcc
	s_cbranch_execz .LBB0_1783
	v_ashrrev_i32_e32 v9, 31, v8
	v_lshlrev_b64 v[10:11], 7, v[8:9]
	v_lshl_add_u64 v[6:7], v[6:7], 0, v[10:11]
	v_lshl_add_u64 v[10:11], v[4:5], 0, v[10:11]
	global_load_dwordx4 v[28:31], v[6:7], off
	s_nop 0
	global_load_dwordx4 v[32:35], v[10:11], off
	v_lshlrev_b32_e32 v14, 1, v8
	v_lshlrev_b32_e32 v9, 7, v8
	v_bfe_u32 v8, v8, 2, 2
	v_and_b32_e32 v14, 4, v14
	v_bitop3_b32 v3, v14, v3, v8 bitop3:0x36
	v_lshl_or_b32 v3, v3, 4, v9
	v_add_u32_e32 v37, 0, v3
.LBB0_1783:
	s_or_b64 exec, exec, s[4:5]
	s_ashr_i32 s10, s16, 3
	v_mov_b32_e32 v3, s10
	s_movk_i32 s4, 0xffe0
	s_lshl_b32 s5, s73, 6
	v_bfi_b32 v102, s4, v3, v92
	v_add_u32_e32 v150, s5, v102
	v_ashrrev_i32_e32 v151, 31, v150
	s_and_b32 s14, s13, 3
	v_lshl_add_u64 v[148:149], v[150:151], 0, s[0:1]
	v_lshlrev_b64 v[4:5], 10, v[148:149]
	s_or_b32 s11, s14, s18
	v_lshrrev_b32_e32 v94, 5, v71
	v_lshl_add_u64 v[4:5], s[92:93], 0, v[4:5]
	s_lshl_b32 s76, s11, 7
	v_lshl_add_u64 v[4:5], v[4:5], 0, s[76:77]
	v_lshlrev_b32_e32 v6, 4, v94
	v_mov_b32_e32 v7, v2
	v_lshl_add_u64 v[4:5], v[4:5], 0, v[6:7]
	global_load_dwordx4 v[114:117], v[4:5], off
	global_load_dwordx4 v[118:121], v[4:5], off offset:32
	global_load_dwordx4 v[122:125], v[4:5], off offset:64
	global_load_dwordx4 v[126:129], v[4:5], off offset:96
	v_lshlrev_b64 v[4:5], 7, v[148:149]
	v_lshl_add_u64 v[4:5], s[58:59], 0, v[4:5]
	s_mul_i32 s76, s11, 12
	s_lshl_b32 s0, s11, 2
	v_readlane_b32 s16, v253, 36
	v_lshl_add_u64 v[4:5], v[4:5], 0, s[76:77]
	v_mov_b32_e32 v3, s0
	v_readlane_b32 s20, v253, 40
	v_readlane_b32 s21, v253, 41
	global_load_dwordx3 v[142:144], v[4:5], off
	v_and_b32_e32 v103, 31, v92
	v_bfe_u32 v96, v92, 2, 2
	v_lshlrev_b32_e32 v97, 7, v103
	v_or_b32_e32 v75, 2, v94
	global_load_dword v95, v3, s[20:21] offset:992
	v_lshlrev_b32_e32 v3, 1, v92
	v_and_b32_e32 v3, 4, v3
	v_bitop3_b32 v4, v3, v94, v96 bitop3:0x36
	v_add_u32_e32 v12, 0, v97
	v_lshlrev_b32_e32 v98, 4, v4
	v_bitop3_b32 v4, v3, v75, v96 bitop3:0x36
	v_lshlrev_b32_e32 v99, 4, v4
	v_or_b32_e32 v4, 4, v94
	v_add_u32_e32 v18, v12, v98
	s_waitcnt vmcnt(6)
	v_ashrrev_i32_e32 v38, 3, v92
	v_cmp_gt_i32_e32 vcc, s6, v38
	s_and_saveexec_b64 s[100:101], vcc
	ds_write_b128 v36, v[20:23]
	ds_write_b128 v36, v[24:27] offset:16384
	s_or_b64 exec, exec, s[100:101]
	v_add_u32_e32 v38, 64, v38
	v_cmp_gt_i32_e32 vcc, s6, v38
	s_and_saveexec_b64 s[100:101], vcc
	ds_write_b128 v37, v[28:31]
	ds_write_b128 v37, v[32:35] offset:16384
	s_or_b64 exec, exec, s[100:101]
	s_waitcnt vmcnt(0) lgkmcnt(0)
	s_barrier
	v_bitop3_b32 v8, v3, v4, v96 bitop3:0x36
	ds_read_b128 v[4:7], v18
	v_lshlrev_b32_e32 v100, 4, v8
	v_or_b32_e32 v8, 6, v94
	v_add_u32_e32 v19, v12, v99
	v_bitop3_b32 v3, v3, v8, v96 bitop3:0x36
	ds_read_b128 v[8:11], v19
	v_add_u32_e32 v68, v12, v100
	v_lshlrev_b32_e32 v101, 4, v3
	v_add_u32_e32 v69, v12, v101
	s_mov_b32 s76, s77
	s_mov_b32 s78, s77
	s_mov_b32 s79, s77
	s_mov_b32 s80, s77
	s_mov_b32 s81, s77
	s_mov_b32 s82, s77
	s_mov_b32 s83, s77
	s_mov_b32 s84, s77
	s_mov_b32 s85, s77
	s_mov_b32 s86, s77
	s_mov_b32 s87, s77
	s_mov_b32 s88, s77
	s_mov_b32 s89, s77
	s_mov_b32 s90, s77
	s_mov_b32 s91, s77
	v_mov_b64_e32 v[36:37], s[76:77]
	s_cmp_gt_u32 s73, 7
	v_writelane_b32 v254, s5, 41
	s_mov_b32 s37, s77
	v_mov_b64_e32 v[38:39], s[78:79]
	v_mov_b64_e32 v[40:41], s[80:81]
	v_mov_b64_e32 v[42:43], s[82:83]
	v_mov_b64_e32 v[44:45], s[84:85]
	v_mov_b64_e32 v[46:47], s[86:87]
	v_mov_b64_e32 v[48:49], s[88:89]
	v_mov_b64_e32 v[50:51], s[90:91]
	s_cselect_b64 s[6:7], -1, 0
	s_cmp_lt_u32 s73, 8
	v_readlane_b32 s17, v253, 37
	v_readlane_b32 s18, v253, 38
	v_readlane_b32 s19, v253, 39
	s_waitcnt lgkmcnt(1)
	v_mfma_f32_32x32x16_bf16 v[52:67], v[4:7], v[114:117], 0
	ds_read_b128 v[4:7], v68
	v_readlane_b32 s22, v253, 42
	v_readlane_b32 s23, v253, 43
	v_readlane_b32 s24, v253, 44
	v_readlane_b32 s25, v253, 45
	v_readlane_b32 s26, v253, 46
	v_readlane_b32 s27, v253, 47
	s_waitcnt lgkmcnt(1)
	v_mfma_f32_32x32x16_bf16 v[52:67], v[8:11], v[118:121], v[52:67]
	ds_read_b128 v[8:11], v69
	v_readlane_b32 s28, v253, 48
	v_readlane_b32 s29, v253, 49
	v_readlane_b32 s30, v253, 50
	v_readlane_b32 s31, v253, 51
	s_waitcnt lgkmcnt(1)
	v_mfma_f32_32x32x16_bf16 v[52:67], v[4:7], v[122:125], v[52:67]
	s_waitcnt lgkmcnt(0)
	v_mfma_f32_32x32x16_bf16 v[52:67], v[8:11], v[126:129], v[52:67]
	s_cbranch_scc1 .LBB0_1785
	ds_read_b128 v[4:7], v18 offset:4096
	ds_read_b128 v[8:11], v19 offset:4096
	s_waitcnt lgkmcnt(1)
	v_mfma_f32_32x32x16_bf16 v[36:51], v[4:7], v[114:117], 0
	s_waitcnt lgkmcnt(0)
	v_mfma_f32_32x32x16_bf16 v[36:51], v[8:11], v[118:121], v[36:51]
	ds_read_b128 v[4:7], v68 offset:4096
	ds_read_b128 v[8:11], v69 offset:4096
	s_waitcnt lgkmcnt(1)
	v_mfma_f32_32x32x16_bf16 v[36:51], v[4:7], v[122:125], v[36:51]
	s_waitcnt lgkmcnt(0)
	v_mfma_f32_32x32x16_bf16 v[36:51], v[8:11], v[126:129], v[36:51]
